# v19 + P5 epilogue defers 6 of 16 Z stores per wave into the next unit's first K-loop super-phases (data held in v228-251, per-wait vmcnt 20/22/12/10)
# baseline (speedup 1.0000x reference)
; #define PG8_STAGE(bufoff, gbase, voff) do { _Pragma("unroll") for (int _i = 0; _i < 2; ++_i) \
;         __builtin_amdgcn_global_load_lds((const unsigned*)((const char*)(gbase) + (voff)[_i]), (PG8_LAS unsigned*)(lds + (bufoff) + ldsw + _i * 8192), 16, 0, 0); } while (0)
; #define PG8_WAIT_V(n) asm volatile("s_waitcnt vmcnt(" #n ")" ::: "memory")
; #define PG8_BAR __builtin_amdgcn_s_barrier()
; template <class Epi, class Sched, bool ALIGN_EPI = false, bool SP2 = false>
; __device__ __forceinline__ void gemm_phase(PG8_LAS unsigned char* lds, const Gemm g, const Sched& S, const Epi& E) {
;     ...
;     const unsigned ldsw = (unsigned)wid * 1024u;
;     const int aoff = lds_byte(wr * 64 + fr, fq * 8), boff = lds_byte(wc * 32 + fr, fq * 8);
;     ...
;         PG8_STAGE(PG8_SB(1, 0), cB + kstep, voffB); PG8_STAGE(PG8_SA(1, 0), cA + kstep, voffA); PG8_STAGE(PG8_SB(1, 1), cB + hstep + kstep, voffB);
;         PG8_WAIT_V(6); PG8_BAR;
.LBB0_1534:
	s_and_b64 s[8:9], s[70:71], exec
	s_cselect_b32 s48, 0xf5, s3
	s_add_u32 s8, s86, 0x1ed00000
	s_addc_u32 s9, s87, 0
	s_lshl_b32 s14, s14, 5
	s_and_b32 s22, s14, 0x60
	s_mov_b64 s[14:15], 0x80
	s_add_i32 m0, s29, 0x18000
	v_lshl_add_u64 v[6:7], v[6:7], 0, s[14:15]
	s_lshl_b32 s17, s16, 13
	s_lshl_b32 s23, s22, 7
	s_waitcnt vmcnt(2)
	s_barrier
	global_load_lds_dwordx4 v[6:7], off
	v_lshl_add_u64 v[4:5], v[4:5], 0, s[14:15]
	s_add_i32 m0, s29, 0x1a000
	s_add_i32 s49, s29, 0x8000
	s_add_i32 s50, s29, 0xa000
	global_load_lds_dwordx4 v[4:5], off
	v_lshl_add_u64 v[0:1], v[0:1], 0, s[14:15]
	s_mov_b32 m0, s49
	s_add_u32 s18, s34, 0x40080
	global_load_lds_dwordx4 v[0:1], off
	v_lshl_add_u64 v[0:1], v[2:3], 0, s[14:15]
	s_mov_b32 m0, s50
	s_addc_u32 s19, s35, 0
	global_load_lds_dwordx4 v[0:1], off
	s_add_i32 m0, s29, 0x1c000
	v_lshl_add_u64 v[0:1], s[18:19], 0, v[132:133]
	global_load_lds_dwordx4 v[0:1], off
	v_lshl_add_u64 v[0:1], s[18:19], 0, v[128:129]
	s_add_i32 m0, s29, 0x1e000
	s_cmpk_lt_u32 s5, 0x100
	global_load_lds_dwordx4 v[0:1], off
	v_lshrrev_b32_e32 v1, 1, v9
	v_and_b32_e32 v1, 24, v1
	v_and_b32_e32 v0, 15, v9
	v_lshlrev_b32_e32 v2, 1, v1
	v_lshl_or_b32 v148, s16, 6, v0
	v_lshl_or_b32 v0, v0, 6, v2
	v_lshlrev_b32_e32 v2, 2, v9
	v_and_b32_e32 v2, 32, v2
	v_bitop3_b32 v3, v0, s17, v2 bitop3:0xde
	v_bitop3_b32 v149, v0, s23, v2 bitop3:0xde
	v_lshlrev_b32_e32 v0, 14, v13
	v_and_b32_e32 v0, 0xffff8000, v0
	v_or_b32_e32 v150, s22, v1
	v_lshl_add_u32 v0, v12, 11, v0
	v_and_b32_e32 v1, 1, v13
	v_lshl_or_b32 v0, v1, 6, v0
	v_lshl_add_u32 v136, v14, 1, v0
	v_lshlrev_b32_e32 v0, 14, v8
	v_and_b32_e32 v0, 0xffff8000, v0
	s_waitcnt vmcnt(6)
	v_lshl_add_u32 v0, v10, 11, v0
	v_and_b32_e32 v1, 1, v8
	s_cselect_b64 s[16:17], -1, 0
	v_lshl_or_b32 v0, v1, 6, v0
	s_add_i32 s52, 0, 0x10000
	s_add_i32 s53, 0, 0x14000
	s_sext_i32_i8 s60, s4
	s_ashr_i32 s51, s48, 31
	v_mov_b32_e32 v137, v133
	v_lshl_add_u32 v138, v11, 1, v0
	v_mov_b32_e32 v139, v133
	v_mov_b64_e32 v[140:141], 0x1040
	v_mov_b64_e32 v[142:143], 0x103f
	v_add_u32_e32 v151, s52, v149
	v_add_u32_e32 v152, s53, v149
	v_add_u32_e32 v153, 0, v3
	v_mov_b32_e32 v154, 0x358637bd
	s_barrier
	s_mov_b32 s99, 0
	s_add_u32 s72, s8, 0x120000
	s_addc_u32 s73, s9, 0
	s_add_u32 s74, s8, 0x140000
	s_addc_u32 s75, s9, 0
	s_add_u32 s76, s8, 0x160000
	s_addc_u32 s77, s9, 0
	s_branch .LBB0_1537

; #define PG8_STAGE(bufoff, gbase, voff) do { _Pragma("unroll") for (int _i = 0; _i < 2; ++_i) \
;         __builtin_amdgcn_global_load_lds((const unsigned*)((const char*)(gbase) + (voff)[_i]), (PG8_LAS unsigned*)(lds + (bufoff) + ldsw + _i * 8192), 16, 0, 0); } while (0)
; #define PG8_LDA(dst, b, h) do { _Pragma("unroll") for (int m = 0; m < 4; ++m) _Pragma("unroll") for (int k = 0; k < 2; ++k) dst[m][k] = *(const PG8_LAS bf16x8*)(lds + PG8_SA(b, h) + aoff + m * 2048 + k * 1024); } while (0)
; #define PG8_LDB(dst, b, h) do { _Pragma("unroll") for (int n = 0; n < 2; ++n) _Pragma("unroll") for (int k = 0; k < 2; ++k) dst[n][k] = *(const PG8_LAS bf16x8*)(lds + PG8_SB(b, h) + boff + n * 2048 + k * 1024); } while (0)
; #define PG8_MMA(ai, bj, At, Bt) do { __builtin_amdgcn_s_setprio(1); _Pragma("unroll") for (int m = 0; m < 4; ++m) _Pragma("unroll") for (int n = 0; n < 2; ++n) _Pragma("unroll") for (int k = 0; k < 2; ++k) \
;         acc[ai][bj][m][n] = __builtin_amdgcn_mfma_f32_16x16x32_bf16(Bt[n][k], At[m][k], acc[ai][bj][m][n], 0, 0, 0); __builtin_amdgcn_s_setprio(0); } while (0)
; #define PG8_WAIT_V(n) asm volatile("s_waitcnt vmcnt(" #n ")" ::: "memory")
; #define PG8_WAIT_L(n) asm volatile("s_waitcnt lgkmcnt(" #n ")" ::: "memory")
; #define PG8_BAR __builtin_amdgcn_s_barrier()
; #define PG8_SCHED __builtin_amdgcn_sched_barrier(0)
; template <class Epi, class Sched, bool ALIGN_EPI = false, bool SP2 = false>
; __device__ __forceinline__ void gemm_phase(PG8_LAS unsigned char* lds, const Gemm g, const Sched& S, const Epi& E) {
;     ...
;             PG8_LDB(B0, 0, 0); PG8_LDB(B1, 0, 1); PG8_SCHED; PG8_LDA(At, 0, 0); PG8_STAGE(PG8_SA(1, 1), a1 + hstep, voffA);
;             PG8_WAIT_V(8); PG8_WAIT_L(0); PG8_BAR; PG8_MMA(0, 0, At, B0); PG8_MMA(0, 1, At, B1); PG8_BAR; PG8_SCHED;
;             PG8_LDA(At, 0, 1); PG8_STAGE(PG8_SB(0, 0), b2, voffB); PG8_STAGE(PG8_SB(0, 1), b2 + hstep, voffB); PG8_STAGE(PG8_SA(0, 0), a2, voffA);
;             PG8_WAIT_V(8); PG8_WAIT_L(0); PG8_BAR; PG8_MMA(1, 0, At, B0); PG8_MMA(1, 1, At, B1); PG8_BAR; PG8_SCHED;
;     __device__ __forceinline__ void operator()(const f32x4 (&acc)[2][2][4][2], const Unit& u, int wr, int wc, int fr, int fq) const {
;     ...
;                     *(u32x4*)(Z + (size_t)row * FF + cb + bj * 128) = pack8(v0, v1); }
.LBB0_1540:
	ds_read_b128 v[144:147], v151
	ds_read_b128 v[156:159], v151 offset:1024
	ds_read_b128 v[160:163], v151 offset:2048
	ds_read_b128 v[164:167], v151 offset:3072
	ds_read_b128 v[168:171], v152
	ds_read_b128 v[172:175], v152 offset:1024
	ds_read_b128 v[176:179], v152 offset:2048
	ds_read_b128 v[180:183], v152 offset:3072
	s_add_u32 s34, s30, 0xfffc0080
	s_addc_u32 s35, s31, -1
	s_cmp_eq_u32 s65, 12
	s_cselect_b32 s37, s23, s35
	s_cselect_b32 s36, s61, s34
	s_cselect_b32 s35, s19, s64
	s_cselect_b32 s34, s62, s63
	v_lshl_add_u64 v[216:217], s[30:31], 0, v[136:137]
	s_add_i32 m0, s29, 0xc000
	ds_read_b128 v[184:187], v153
	ds_read_b128 v[188:191], v153 offset:1024
	ds_read_b128 v[192:195], v153 offset:2048
	ds_read_b128 v[196:199], v153 offset:3072
	ds_read_b128 v[200:203], v153 offset:4096
	ds_read_b128 v[204:207], v153 offset:5120
	ds_read_b128 v[208:211], v153 offset:6144
	ds_read_b128 v[212:215], v153 offset:7168
	s_cmp_eq_u32 s99, 1
	s_cbranch_scc0 .Lnd_P5_0
	global_store_dwordx4 v227, v[228:231], s[72:73]
	global_store_dwordx4 v227, v[232:235], s[72:73] offset:256
.Lnd_P5_0:
	global_load_lds_dwordx4 v[216:217], off
	v_lshl_add_u64 v[216:217], s[30:31], 0, v[138:139]
	s_add_i32 m0, s29, 0xe000
	s_nop 0
	global_load_lds_dwordx4 v[216:217], off
	s_cmp_eq_u32 s99, 1
	s_cbranch_scc1 .Lrw_P5_0
	s_waitcnt vmcnt(8)
	s_branch .Lrj_P5_0
.Lrw_P5_0:
	s_waitcnt vmcnt(20)
.Lrj_P5_0:
	s_waitcnt lgkmcnt(0)
	s_barrier
	s_setprio 1
	s_waitcnt lgkmcnt(0)
	v_mfma_f32_16x16x32_bf16 v[124:127], v[144:147], v[184:187], v[124:127]
	v_mfma_f32_16x16x32_bf16 v[120:123], v[160:163], v[184:187], v[120:123]
	v_mfma_f32_16x16x32_bf16 v[108:111], v[144:147], v[192:195], v[108:111]
	v_mfma_f32_16x16x32_bf16 v[104:107], v[160:163], v[192:195], v[104:107]
	v_mfma_f32_16x16x32_bf16 v[92:95], v[144:147], v[200:203], v[92:95]
	v_mfma_f32_16x16x32_bf16 v[88:91], v[160:163], v[200:203], v[88:91]
	v_mfma_f32_16x16x32_bf16 v[76:79], v[144:147], v[208:211], v[76:79]
	v_mfma_f32_16x16x32_bf16 v[72:75], v[160:163], v[208:211], v[72:75]
	v_mfma_f32_16x16x32_bf16 v[124:127], v[156:159], v[188:191], v[124:127]
	v_mfma_f32_16x16x32_bf16 v[120:123], v[164:167], v[188:191], v[120:123]
	v_mfma_f32_16x16x32_bf16 v[108:111], v[156:159], v[196:199], v[108:111]
	v_mfma_f32_16x16x32_bf16 v[104:107], v[164:167], v[196:199], v[104:107]
	v_mfma_f32_16x16x32_bf16 v[92:95], v[156:159], v[204:207], v[92:95]
	v_mfma_f32_16x16x32_bf16 v[88:91], v[164:167], v[204:207], v[88:91]
	v_mfma_f32_16x16x32_bf16 v[76:79], v[156:159], v[212:215], v[76:79]
	v_mfma_f32_16x16x32_bf16 v[72:75], v[164:167], v[212:215], v[72:75]
	s_setprio 0
	s_setprio 1
	v_mfma_f32_16x16x32_bf16 v[116:119], v[168:171], v[184:187], v[116:119]
	v_mfma_f32_16x16x32_bf16 v[112:115], v[176:179], v[184:187], v[112:115]
	v_mfma_f32_16x16x32_bf16 v[100:103], v[168:171], v[192:195], v[100:103]
	v_mfma_f32_16x16x32_bf16 v[96:99], v[176:179], v[192:195], v[96:99]
	v_mfma_f32_16x16x32_bf16 v[84:87], v[168:171], v[200:203], v[84:87]
	v_mfma_f32_16x16x32_bf16 v[80:83], v[176:179], v[200:203], v[80:83]
	v_mfma_f32_16x16x32_bf16 v[68:71], v[168:171], v[208:211], v[68:71]
	v_mfma_f32_16x16x32_bf16 v[64:67], v[176:179], v[208:211], v[64:67]
	v_mfma_f32_16x16x32_bf16 v[116:119], v[172:175], v[188:191], v[116:119]
	v_mfma_f32_16x16x32_bf16 v[112:115], v[180:183], v[188:191], v[112:115]
	v_mfma_f32_16x16x32_bf16 v[100:103], v[172:175], v[196:199], v[100:103]
	v_mfma_f32_16x16x32_bf16 v[96:99], v[180:183], v[196:199], v[96:99]
	v_mfma_f32_16x16x32_bf16 v[84:87], v[172:175], v[204:207], v[84:87]
	v_mfma_f32_16x16x32_bf16 v[80:83], v[180:183], v[204:207], v[80:83]
	v_mfma_f32_16x16x32_bf16 v[68:71], v[172:175], v[212:215], v[68:71]
	v_mfma_f32_16x16x32_bf16 v[64:67], v[180:183], v[212:215], v[64:67]
	s_setprio 0
	s_barrier
	s_add_i32 s66, s52, s39
	v_lshl_add_u64 v[216:217], s[34:35], 0, v[132:133]
	s_mov_b32 m0, s66
	ds_read_b128 v[184:187], v153 offset:16384
	ds_read_b128 v[188:191], v153 offset:17408
	ds_read_b128 v[192:195], v153 offset:18432
	ds_read_b128 v[196:199], v153 offset:19456
	ds_read_b128 v[200:203], v153 offset:20480
	ds_read_b128 v[204:207], v153 offset:21504
	ds_read_b128 v[208:211], v153 offset:22528
	ds_read_b128 v[212:215], v153 offset:23552
	s_cmp_eq_u32 s99, 1
	s_cbranch_scc0 .Lnd_P5_1
	global_store_dwordx4 v227, v[236:239], s[74:75]
	global_store_dwordx4 v227, v[240:243], s[74:75] offset:256
.Lnd_P5_1:
	global_load_lds_dwordx4 v[216:217], off
	s_add_i32 m0, s66, 0x2000
	s_add_u32 s66, s34, 0x40000
	v_lshl_add_u64 v[218:219], s[34:35], 0, v[128:129]
	s_addc_u32 s67, s35, 0
	s_add_i32 s68, s53, s39
	global_load_lds_dwordx4 v[218:219], off
	v_lshl_add_u64 v[220:221], s[66:67], 0, v[132:133]
	s_mov_b32 m0, s68
	v_lshl_add_u64 v[222:223], s[36:37], 0, v[130:131]
	global_load_lds_dwordx4 v[220:221], off
	v_lshl_add_u64 v[220:221], s[66:67], 0, v[128:129]
	s_add_i32 m0, s68, 0x2000
	s_nop 0
	global_load_lds_dwordx4 v[220:221], off
	v_lshl_add_u64 v[220:221], s[36:37], 0, v[134:135]
	s_mov_b32 m0, s29
	s_nop 0
	global_load_lds_dwordx4 v[220:221], off
	s_mov_b32 m0, s42
	s_nop 0
	global_load_lds_dwordx4 v[222:223], off
	s_cmp_eq_u32 s99, 1
	s_cbranch_scc1 .Lrw_P5_1
	s_waitcnt vmcnt(8)
	s_branch .Lrj_P5_1
.Lrw_P5_1:
	s_waitcnt vmcnt(22)
; #define PG8_STAGE(bufoff, gbase, voff) do { _Pragma("unroll") for (int _i = 0; _i < 2; ++_i) \
;         __builtin_amdgcn_global_load_lds((const unsigned*)((const char*)(gbase) + (voff)[_i]), (PG8_LAS unsigned*)(lds + (bufoff) + ldsw + _i * 8192), 16, 0, 0); } while (0)
; #define PG8_LDA(dst, b, h) do { _Pragma("unroll") for (int m = 0; m < 4; ++m) _Pragma("unroll") for (int k = 0; k < 2; ++k) dst[m][k] = *(const PG8_LAS bf16x8*)(lds + PG8_SA(b, h) + aoff + m * 2048 + k * 1024); } while (0)
; #define PG8_LDB(dst, b, h) do { _Pragma("unroll") for (int n = 0; n < 2; ++n) _Pragma("unroll") for (int k = 0; k < 2; ++k) dst[n][k] = *(const PG8_LAS bf16x8*)(lds + PG8_SB(b, h) + boff + n * 2048 + k * 1024); } while (0)
; #define PG8_MMA(ai, bj, At, Bt) do { __builtin_amdgcn_s_setprio(1); _Pragma("unroll") for (int m = 0; m < 4; ++m) _Pragma("unroll") for (int n = 0; n < 2; ++n) _Pragma("unroll") for (int k = 0; k < 2; ++k) \
;         acc[ai][bj][m][n] = __builtin_amdgcn_mfma_f32_16x16x32_bf16(Bt[n][k], At[m][k], acc[ai][bj][m][n], 0, 0, 0); __builtin_amdgcn_s_setprio(0); } while (0)
; #define PG8_WAIT_V(n) asm volatile("s_waitcnt vmcnt(" #n ")" ::: "memory")
; #define PG8_WAIT_L(n) asm volatile("s_waitcnt lgkmcnt(" #n ")" ::: "memory")
; #define PG8_BAR __builtin_amdgcn_s_barrier()
; #define PG8_SCHED __builtin_amdgcn_sched_barrier(0)
; __device__ __forceinline__ u32x4 pack8(const f32x4 a, const f32x4 b) { u32x4 w; w.x = cvt_pk_bf16(a[0], a[1]); w.y = cvt_pk_bf16(a[2], a[3]); w.z = cvt_pk_bf16(b[0], b[1]); w.w = cvt_pk_bf16(b[2], b[3]); return w; }
; template <class Epi, class Sched, bool ALIGN_EPI = false, bool SP2 = false>
; __device__ __forceinline__ void gemm_phase(PG8_LAS unsigned char* lds, const Gemm g, const Sched& S, const Epi& E) {
;     ...
;             PG8_WAIT_V(8); PG8_WAIT_L(0); PG8_BAR; PG8_MMA(1, 0, At, B0); PG8_MMA(1, 1, At, B1); PG8_BAR; PG8_SCHED;
;             PG8_LDB(B0, 1, 0); PG8_LDB(B1, 1, 1); PG8_SCHED; PG8_LDA(At, 1, 0); PG8_STAGE(PG8_SA(0, 1), a2 + hstep, voffA);
;             PG8_WAIT_V(8); PG8_WAIT_L(0); PG8_BAR; PG8_MMA(0, 0, At, B0); PG8_MMA(0, 1, At, B1); PG8_BAR; PG8_SCHED;
;     __device__ __forceinline__ void operator()(const f32x4 (&acc)[2][2][4][2], const Unit& u, int wr, int wc, int fr, int fq) const {
;     ...
;                     *(u32x4*)(Z + (size_t)row * FF + cb + bj * 128) = pack8(v0, v1); }
.Lrj_P5_1:
	s_waitcnt lgkmcnt(0)
	s_barrier
	s_setprio 1
	s_waitcnt lgkmcnt(0)
	v_mfma_f32_16x16x32_bf16 v[60:63], v[144:147], v[184:187], v[60:63]
	v_mfma_f32_16x16x32_bf16 v[56:59], v[160:163], v[184:187], v[56:59]
	v_mfma_f32_16x16x32_bf16 v[44:47], v[144:147], v[192:195], v[44:47]
	v_mfma_f32_16x16x32_bf16 v[40:43], v[160:163], v[192:195], v[40:43]
	v_mfma_f32_16x16x32_bf16 v[28:31], v[144:147], v[200:203], v[28:31]
	v_mfma_f32_16x16x32_bf16 v[24:27], v[160:163], v[200:203], v[24:27]
	v_mfma_f32_16x16x32_bf16 v[12:15], v[144:147], v[208:211], v[12:15]
	v_mfma_f32_16x16x32_bf16 v[8:11], v[160:163], v[208:211], v[8:11]
	v_mfma_f32_16x16x32_bf16 v[60:63], v[156:159], v[188:191], v[60:63]
	v_mfma_f32_16x16x32_bf16 v[56:59], v[164:167], v[188:191], v[56:59]
	v_mfma_f32_16x16x32_bf16 v[44:47], v[156:159], v[196:199], v[44:47]
	v_mfma_f32_16x16x32_bf16 v[40:43], v[164:167], v[196:199], v[40:43]
	v_mfma_f32_16x16x32_bf16 v[28:31], v[156:159], v[204:207], v[28:31]
	v_mfma_f32_16x16x32_bf16 v[24:27], v[164:167], v[204:207], v[24:27]
	v_mfma_f32_16x16x32_bf16 v[12:15], v[156:159], v[212:215], v[12:15]
	v_mfma_f32_16x16x32_bf16 v[8:11], v[164:167], v[212:215], v[8:11]
	s_setprio 0
	s_setprio 1
	v_mfma_f32_16x16x32_bf16 v[52:55], v[168:171], v[184:187], v[52:55]
	v_mfma_f32_16x16x32_bf16 v[48:51], v[176:179], v[184:187], v[48:51]
	v_mfma_f32_16x16x32_bf16 v[36:39], v[168:171], v[192:195], v[36:39]
	v_mfma_f32_16x16x32_bf16 v[32:35], v[176:179], v[192:195], v[32:35]
	v_mfma_f32_16x16x32_bf16 v[20:23], v[168:171], v[200:203], v[20:23]
	v_mfma_f32_16x16x32_bf16 v[16:19], v[176:179], v[200:203], v[16:19]
	v_mfma_f32_16x16x32_bf16 v[4:7], v[168:171], v[208:211], v[4:7]
	v_mfma_f32_16x16x32_bf16 v[0:3], v[176:179], v[208:211], v[0:3]
	v_mfma_f32_16x16x32_bf16 v[52:55], v[172:175], v[188:191], v[52:55]
	v_mfma_f32_16x16x32_bf16 v[48:51], v[180:183], v[188:191], v[48:51]
	v_mfma_f32_16x16x32_bf16 v[36:39], v[172:175], v[196:199], v[36:39]
	v_mfma_f32_16x16x32_bf16 v[32:35], v[180:183], v[196:199], v[32:35]
	v_mfma_f32_16x16x32_bf16 v[20:23], v[172:175], v[204:207], v[20:23]
	v_mfma_f32_16x16x32_bf16 v[16:19], v[180:183], v[204:207], v[16:19]
	v_mfma_f32_16x16x32_bf16 v[4:7], v[172:175], v[212:215], v[4:7]
	v_mfma_f32_16x16x32_bf16 v[0:3], v[180:183], v[212:215], v[0:3]
	s_setprio 0
	s_barrier
	s_add_i32 s66, 0, 0x18000
	v_add_u32_e32 v155, s66, v149
	s_add_i32 s67, 0, 0x1c000
	ds_read_b128 v[144:147], v155
	ds_read_b128 v[156:159], v155 offset:1024
	ds_read_b128 v[160:163], v155 offset:2048
	ds_read_b128 v[164:167], v155 offset:3072
	v_add_u32_e32 v155, s67, v149
	ds_read_b128 v[168:171], v155
	ds_read_b128 v[172:175], v155 offset:1024
	ds_read_b128 v[176:179], v155 offset:2048
	ds_read_b128 v[180:183], v155 offset:3072
	s_add_u32 s36, s36, 0x40000
	s_addc_u32 s37, s37, 0
	s_mov_b32 m0, s43
	v_lshl_add_u64 v[224:225], s[36:37], 0, v[134:135]
	ds_read_b128 v[184:187], v153 offset:32768
	ds_read_b128 v[188:191], v153 offset:33792
	ds_read_b128 v[192:195], v153 offset:34816
	ds_read_b128 v[196:199], v153 offset:35840
	ds_read_b128 v[200:203], v153 offset:36864
	ds_read_b128 v[204:207], v153 offset:37888
	ds_read_b128 v[208:211], v153 offset:38912
	ds_read_b128 v[212:215], v153 offset:39936
	s_cmp_eq_u32 s99, 1
	s_cbranch_scc0 .Lnd_P5_2
	global_store_dwordx4 v227, v[244:247], s[76:77]
	global_store_dwordx4 v227, v[248:251], s[76:77] offset:256
.Lnd_P5_2:
	global_load_lds_dwordx4 v[224:225], off
	v_lshl_add_u64 v[224:225], s[36:37], 0, v[130:131]
	s_mov_b32 m0, s46
	s_nop 0
	global_load_lds_dwordx4 v[224:225], off
	s_cmp_eq_u32 s99, 1
	s_cbranch_scc1 .Lrw_P5_2
	s_waitcnt vmcnt(8)
	s_branch .Lrj_P5_2
.Lrw_P5_2:
	s_waitcnt vmcnt(12)
.Lrj_P5_2:
	s_waitcnt lgkmcnt(0)
	s_barrier
	s_setprio 1
	s_waitcnt lgkmcnt(0)
	v_mfma_f32_16x16x32_bf16 v[124:127], v[144:147], v[184:187], v[124:127]
	v_mfma_f32_16x16x32_bf16 v[120:123], v[160:163], v[184:187], v[120:123]
	v_mfma_f32_16x16x32_bf16 v[108:111], v[144:147], v[192:195], v[108:111]
	v_mfma_f32_16x16x32_bf16 v[104:107], v[160:163], v[192:195], v[104:107]
	v_mfma_f32_16x16x32_bf16 v[92:95], v[144:147], v[200:203], v[92:95]
	v_mfma_f32_16x16x32_bf16 v[88:91], v[160:163], v[200:203], v[88:91]
	v_mfma_f32_16x16x32_bf16 v[76:79], v[144:147], v[208:211], v[76:79]
	v_mfma_f32_16x16x32_bf16 v[72:75], v[160:163], v[208:211], v[72:75]
	v_mfma_f32_16x16x32_bf16 v[124:127], v[156:159], v[188:191], v[124:127]
	v_mfma_f32_16x16x32_bf16 v[120:123], v[164:167], v[188:191], v[120:123]
	v_mfma_f32_16x16x32_bf16 v[108:111], v[156:159], v[196:199], v[108:111]
	v_mfma_f32_16x16x32_bf16 v[104:107], v[164:167], v[196:199], v[104:107]
	v_mfma_f32_16x16x32_bf16 v[92:95], v[156:159], v[204:207], v[92:95]
	v_mfma_f32_16x16x32_bf16 v[88:91], v[164:167], v[204:207], v[88:91]
	v_mfma_f32_16x16x32_bf16 v[76:79], v[156:159], v[212:215], v[76:79]
	v_mfma_f32_16x16x32_bf16 v[72:75], v[164:167], v[212:215], v[72:75]
	s_setprio 0
	s_setprio 1
	v_mfma_f32_16x16x32_bf16 v[116:119], v[168:171], v[184:187], v[116:119]
	v_mfma_f32_16x16x32_bf16 v[112:115], v[176:179], v[184:187], v[112:115]
	v_mfma_f32_16x16x32_bf16 v[100:103], v[168:171], v[192:195], v[100:103]
	v_mfma_f32_16x16x32_bf16 v[96:99], v[176:179], v[192:195], v[96:99]
	v_mfma_f32_16x16x32_bf16 v[84:87], v[168:171], v[200:203], v[84:87]
	v_mfma_f32_16x16x32_bf16 v[80:83], v[176:179], v[200:203], v[80:83]
	v_mfma_f32_16x16x32_bf16 v[68:71], v[168:171], v[208:211], v[68:71]
	v_mfma_f32_16x16x32_bf16 v[64:67], v[176:179], v[208:211], v[64:67]
	v_mfma_f32_16x16x32_bf16 v[116:119], v[172:175], v[188:191], v[116:119]
	v_mfma_f32_16x16x32_bf16 v[112:115], v[180:183], v[188:191], v[112:115]
	v_mfma_f32_16x16x32_bf16 v[100:103], v[172:175], v[196:199], v[100:103]
	v_mfma_f32_16x16x32_bf16 v[96:99], v[180:183], v[196:199], v[96:99]
	v_mfma_f32_16x16x32_bf16 v[84:87], v[172:175], v[204:207], v[84:87]
	v_mfma_f32_16x16x32_bf16 v[80:83], v[180:183], v[204:207], v[80:83]
	v_mfma_f32_16x16x32_bf16 v[68:71], v[172:175], v[212:215], v[68:71]
	v_mfma_f32_16x16x32_bf16 v[64:67], v[180:183], v[212:215], v[64:67]
	s_setprio 0
	s_barrier
; #define PG8_STAGE(bufoff, gbase, voff) do { _Pragma("unroll") for (int _i = 0; _i < 2; ++_i) \
;         __builtin_amdgcn_global_load_lds((const unsigned*)((const char*)(gbase) + (voff)[_i]), (PG8_LAS unsigned*)(lds + (bufoff) + ldsw + _i * 8192), 16, 0, 0); } while (0)
; #define PG8_LDA(dst, b, h) do { _Pragma("unroll") for (int m = 0; m < 4; ++m) _Pragma("unroll") for (int k = 0; k < 2; ++k) dst[m][k] = *(const PG8_LAS bf16x8*)(lds + PG8_SA(b, h) + aoff + m * 2048 + k * 1024); } while (0)
; #define PG8_MMA(ai, bj, At, Bt) do { __builtin_amdgcn_s_setprio(1); _Pragma("unroll") for (int m = 0; m < 4; ++m) _Pragma("unroll") for (int n = 0; n < 2; ++n) _Pragma("unroll") for (int k = 0; k < 2; ++k) \
;         acc[ai][bj][m][n] = __builtin_amdgcn_mfma_f32_16x16x32_bf16(Bt[n][k], At[m][k], acc[ai][bj][m][n], 0, 0, 0); __builtin_amdgcn_s_setprio(0); } while (0)
; #define PG8_WAIT_V(n) asm volatile("s_waitcnt vmcnt(" #n ")" ::: "memory")
; #define PG8_WAIT_L(n) asm volatile("s_waitcnt lgkmcnt(" #n ")" ::: "memory")
; #define PG8_BAR __builtin_amdgcn_s_barrier()
; #define PG8_SCHED __builtin_amdgcn_sched_barrier(0)
; template <class Epi, class Sched, bool ALIGN_EPI = false, bool SP2 = false>
; __device__ __forceinline__ void gemm_phase(PG8_LAS unsigned char* lds, const Gemm g, const Sched& S, const Epi& E) {
;     ...
;             PG8_LDA(At, 1, 1); PG8_STAGE(PG8_SB(1, 0), b3, voffB); PG8_STAGE(PG8_SB(1, 1), b3 + hstep, voffB); PG8_STAGE(PG8_SA(1, 0), a3, voffA);
;             PG8_WAIT_V(8); PG8_WAIT_L(0); PG8_BAR; PG8_MMA(1, 0, At, B0); PG8_MMA(1, 1, At, B1); PG8_BAR; PG8_SCHED;
;     __device__ __forceinline__ void operator()(const f32x4 (&acc)[2][2][4][2], const Unit& u, int wr, int wc, int fr, int fq) const {
;     ...
;             for (int m = 0; m < 4; ++m) { const int row = rbase + ai * 128 + m * 16; const f32x4* sp = (const f32x4*)(SSP + (size_t)row * 16);
;                 const f32x4 s4 = (sp[0] + sp[1]) + (sp[2] + sp[3]); const float rstd = __builtin_amdgcn_rsqf(((s4[0] + s4[1]) + (s4[2] + s4[3])) * (1.0f / 1024.0f) + EPS);
	s_add_i32 s36, s66, s39
	v_lshl_add_u64 v[216:217], v[216:217], 0, s[14:15]
	s_mov_b32 m0, s36
	ds_read_b128 v[184:187], v153 offset:49152
	ds_read_b128 v[188:191], v153 offset:50176
	ds_read_b128 v[192:195], v153 offset:51200
	ds_read_b128 v[196:199], v153 offset:52224
	ds_read_b128 v[200:203], v153 offset:53248
	ds_read_b128 v[204:207], v153 offset:54272
	ds_read_b128 v[208:211], v153 offset:55296
	ds_read_b128 v[212:215], v153 offset:56320
	global_load_lds_dwordx4 v[216:217], off
	s_add_i32 m0, s36, 0x2000
	s_add_u32 s34, s34, 0x40080
	v_lshl_add_u64 v[216:217], v[218:219], 0, s[14:15]
	s_addc_u32 s35, s35, 0
	s_add_i32 s36, s67, s39
	global_load_lds_dwordx4 v[216:217], off
	v_lshl_add_u64 v[216:217], s[34:35], 0, v[132:133]
	s_mov_b32 m0, s36
	s_nop 0
	global_load_lds_dwordx4 v[216:217], off
	v_lshl_add_u64 v[216:217], s[34:35], 0, v[128:129]
	s_add_i32 m0, s36, 0x2000
	s_nop 0
	global_load_lds_dwordx4 v[216:217], off
	v_lshl_add_u64 v[216:217], v[220:221], 0, s[14:15]
	s_mov_b32 m0, s49
	s_nop 0
	global_load_lds_dwordx4 v[216:217], off
	v_lshl_add_u64 v[216:217], v[222:223], 0, s[14:15]
	s_mov_b32 m0, s50
	s_nop 0
	global_load_lds_dwordx4 v[216:217], off
	s_cmp_eq_u32 s99, 1
	s_cbranch_scc1 .Lrw_P5_3
	s_waitcnt vmcnt(8)
	s_branch .Lrj_P5_3
.Lrw_P5_3:
	s_waitcnt vmcnt(10)
.Lrj_P5_3:
	s_waitcnt lgkmcnt(0)
	s_barrier
	s_setprio 1
	s_waitcnt lgkmcnt(0)
	v_mfma_f32_16x16x32_bf16 v[60:63], v[144:147], v[184:187], v[60:63]
	v_mfma_f32_16x16x32_bf16 v[56:59], v[160:163], v[184:187], v[56:59]
	v_mfma_f32_16x16x32_bf16 v[44:47], v[144:147], v[192:195], v[44:47]
	v_mfma_f32_16x16x32_bf16 v[40:43], v[160:163], v[192:195], v[40:43]
	v_mfma_f32_16x16x32_bf16 v[28:31], v[144:147], v[200:203], v[28:31]
	v_mfma_f32_16x16x32_bf16 v[24:27], v[160:163], v[200:203], v[24:27]
	v_mfma_f32_16x16x32_bf16 v[12:15], v[144:147], v[208:211], v[12:15]
	v_mfma_f32_16x16x32_bf16 v[8:11], v[160:163], v[208:211], v[8:11]
	v_mfma_f32_16x16x32_bf16 v[60:63], v[156:159], v[188:191], v[60:63]
	v_mfma_f32_16x16x32_bf16 v[56:59], v[164:167], v[188:191], v[56:59]
	v_mfma_f32_16x16x32_bf16 v[44:47], v[156:159], v[196:199], v[44:47]
	v_mfma_f32_16x16x32_bf16 v[40:43], v[164:167], v[196:199], v[40:43]
	v_mfma_f32_16x16x32_bf16 v[28:31], v[156:159], v[204:207], v[28:31]
	v_mfma_f32_16x16x32_bf16 v[24:27], v[164:167], v[204:207], v[24:27]
	v_mfma_f32_16x16x32_bf16 v[12:15], v[156:159], v[212:215], v[12:15]
	v_mfma_f32_16x16x32_bf16 v[8:11], v[164:167], v[212:215], v[8:11]
	s_setprio 0
	s_setprio 1
	v_mfma_f32_16x16x32_bf16 v[52:55], v[168:171], v[184:187], v[52:55]
	v_mfma_f32_16x16x32_bf16 v[48:51], v[176:179], v[184:187], v[48:51]
	v_mfma_f32_16x16x32_bf16 v[36:39], v[168:171], v[192:195], v[36:39]
	v_mfma_f32_16x16x32_bf16 v[32:35], v[176:179], v[192:195], v[32:35]
	v_mfma_f32_16x16x32_bf16 v[20:23], v[168:171], v[200:203], v[20:23]
	v_mfma_f32_16x16x32_bf16 v[16:19], v[176:179], v[200:203], v[16:19]
	v_mfma_f32_16x16x32_bf16 v[4:7], v[168:171], v[208:211], v[4:7]
	v_mfma_f32_16x16x32_bf16 v[0:3], v[176:179], v[208:211], v[0:3]
	v_mfma_f32_16x16x32_bf16 v[52:55], v[172:175], v[188:191], v[52:55]
	v_mfma_f32_16x16x32_bf16 v[48:51], v[180:183], v[188:191], v[48:51]
	v_mfma_f32_16x16x32_bf16 v[36:39], v[172:175], v[196:199], v[36:39]
	v_mfma_f32_16x16x32_bf16 v[32:35], v[180:183], v[196:199], v[32:35]
	v_mfma_f32_16x16x32_bf16 v[20:23], v[172:175], v[204:207], v[20:23]
	v_mfma_f32_16x16x32_bf16 v[16:19], v[180:183], v[204:207], v[16:19]
	v_mfma_f32_16x16x32_bf16 v[4:7], v[172:175], v[212:215], v[4:7]
	v_mfma_f32_16x16x32_bf16 v[0:3], v[180:183], v[212:215], v[0:3]
	s_setprio 0
	s_barrier
	s_mov_b32 s99, 0
	s_add_i32 s65, s65, 2
	s_add_u32 s30, s30, 0x100
	s_addc_u32 s31, s31, 0
	s_add_u32 s63, s63, 0x100
	s_addc_u32 s64, s64, 0
	s_cmp_gt_u32 s65, 13
	s_cbranch_scc0 .LBB0_1540
	v_lshl_add_u32 v146, s28, 8, v148
	v_ashrrev_i32_e32 v147, 31, v146
	v_lshlrev_b64 v[144:145], 6, v[146:147]
	v_lshl_add_u64 v[144:145], s[12:13], 0, v[144:145]
	global_load_dwordx4 v[156:159], v[144:145], off
	global_load_dwordx4 v[160:163], v[144:145], off offset:16
	global_load_dwordx4 v[164:167], v[144:145], off offset:32
	global_load_dwordx4 v[168:171], v[144:145], off offset:48
	global_load_dwordx4 v[172:175], v[144:145], off offset:1024
	global_load_dwordx4 v[176:179], v[144:145], off offset:1040
	global_load_dwordx4 v[180:183], v[144:145], off offset:1056
	global_load_dwordx4 v[184:187], v[144:145], off offset:1072
	global_load_dwordx4 v[188:191], v[144:145], off offset:2048
	global_load_dwordx4 v[192:195], v[144:145], off offset:2064
	global_load_dwordx4 v[196:199], v[144:145], off offset:2080
	global_load_dwordx4 v[200:203], v[144:145], off offset:2096
	global_load_dwordx4 v[204:207], v[144:145], off offset:3072
	global_load_dwordx4 v[208:211], v[144:145], off offset:3088
	global_load_dwordx4 v[212:215], v[144:145], off offset:3104
	global_load_dwordx4 v[216:219], v[144:145], off offset:3120
	s_and_b64 vcc, exec, s[16:17]
	s_cbranch_vccz .LBB0_1543
	s_barrier
; __device__ __forceinline__ u32x4 pack8(const f32x4 a, const f32x4 b) { u32x4 w; w.x = cvt_pk_bf16(a[0], a[1]); w.y = cvt_pk_bf16(a[2], a[3]); w.z = cvt_pk_bf16(b[0], b[1]); w.w = cvt_pk_bf16(b[2], b[3]); return w; }
;     __device__ __forceinline__ void operator()(const f32x4 (&acc)[2][2][4][2], const Unit& u, int wr, int wc, int fr, int fq) const {
;     ...
;             for (int m = 0; m < 4; ++m) { const int row = rbase + ai * 128 + m * 16; const f32x4* sp = (const f32x4*)(SSP + (size_t)row * 16);
;                 const f32x4 s4 = (sp[0] + sp[1]) + (sp[2] + sp[3]); const float rstd = __builtin_amdgcn_rsqf(((s4[0] + s4[1]) + (s4[2] + s4[3])) * (1.0f / 1024.0f) + EPS);
; #pragma unroll
;                 for (int bj = 0; bj < 2; ++bj) { f32x4 v0 = acc[ai][bj][m][0] * rstd, v1 = acc[ai][bj][m][1] * rstd;
; #pragma unroll
;                     for (int i = 0; i < 4; ++i) { const float a = fmaxf(v0[i], 0.f), b = fmaxf(v1[i], 0.f); v0[i] = a * a; v1[i] = b * b; }
;                     *(u32x4*)(Z + (size_t)row * FF + cb + bj * 128) = pack8(v0, v1); }
.LBB0_1543:
	v_lshlrev_b64 v[220:221], 13, v[146:147]
	v_lshl_or_b32 v222, s60, 8, v150
	v_ashrrev_i32_e32 v223, 31, v222
	v_lshlrev_b64 v[222:223], 1, v[222:223]
	v_lshl_add_u32 v227, v146, 13, v222
	v_lshl_add_u64 v[220:221], s[8:9], 0, v[220:221]
	v_lshl_add_u64 v[220:221], v[220:221], 0, v[222:223]
	v_mov_b64_e32 v[224:225], v[220:221]
	s_mov_b64 s[98:99], 0x2000
	s_mov_b64 s[100:101], 0xa0000
	v_lshl_add_u64 v[222:223], v[144:145], 0, s[98:99]
	s_mov_b64 s[98:99], 0x20000
	s_waitcnt vmcnt(12)
	v_pk_add_f32 v[156:157], v[156:157], v[160:161]
	v_pk_add_f32 v[158:159], v[158:159], v[162:163]
	v_pk_add_f32 v[164:165], v[164:165], v[168:169]
	v_pk_add_f32 v[166:167], v[166:167], v[170:171]
	v_pk_add_f32 v[156:157], v[156:157], v[164:165]
	v_pk_add_f32 v[158:159], v[158:159], v[166:167]
	v_add_f32_e32 v156, v156, v157
	v_add_f32_e32 v158, v158, v159
	v_add_f32_e32 v156, v156, v158
	v_fmamk_f32 v156, v156, 0x3a800000, v154
	v_rsq_f32_e32 v144, v156
	s_waitcnt vmcnt(8)
	v_pk_add_f32 v[172:173], v[172:173], v[176:177]
	v_pk_add_f32 v[174:175], v[174:175], v[178:179]
	v_pk_add_f32 v[180:181], v[180:181], v[184:185]
	v_pk_add_f32 v[182:183], v[182:183], v[186:187]
	v_pk_add_f32 v[172:173], v[172:173], v[180:181]
	v_pk_add_f32 v[174:175], v[174:175], v[182:183]
	v_add_f32_e32 v172, v172, v173
	v_add_f32_e32 v174, v174, v175
	v_add_f32_e32 v172, v172, v174
	v_fmamk_f32 v172, v172, 0x3a800000, v154
	v_rsq_f32_e32 v145, v172
	s_waitcnt vmcnt(4)
	v_pk_add_f32 v[188:189], v[188:189], v[192:193]
	v_pk_add_f32 v[190:191], v[190:191], v[194:195]
	v_pk_add_f32 v[196:197], v[196:197], v[200:201]
	v_pk_add_f32 v[198:199], v[198:199], v[202:203]
	v_pk_add_f32 v[188:189], v[188:189], v[196:197]
	v_pk_add_f32 v[190:191], v[190:191], v[198:199]
	v_add_f32_e32 v188, v188, v189
	v_add_f32_e32 v190, v190, v191
	v_add_f32_e32 v188, v188, v190
	v_fmamk_f32 v188, v188, 0x3a800000, v154
	v_rsq_f32_e32 v146, v188
	s_waitcnt vmcnt(0)
	v_pk_add_f32 v[204:205], v[204:205], v[208:209]
	v_pk_add_f32 v[206:207], v[206:207], v[210:211]
	v_pk_add_f32 v[212:213], v[212:213], v[216:217]
	v_pk_add_f32 v[214:215], v[214:215], v[218:219]
	v_pk_add_f32 v[204:205], v[204:205], v[212:213]
	v_pk_add_f32 v[206:207], v[206:207], v[214:215]
	v_add_f32_e32 v204, v204, v205
	v_add_f32_e32 v206, v206, v207
	v_add_f32_e32 v204, v204, v206
	v_fmamk_f32 v204, v204, 0x3a800000, v154
	v_rsq_f32_e32 v147, v204
	global_load_dwordx4 v[156:159], v[222:223], off
	global_load_dwordx4 v[160:163], v[222:223], off offset:16
	global_load_dwordx4 v[164:167], v[222:223], off offset:32
	global_load_dwordx4 v[168:171], v[222:223], off offset:48
	global_load_dwordx4 v[172:175], v[222:223], off offset:1024
	global_load_dwordx4 v[176:179], v[222:223], off offset:1040
	global_load_dwordx4 v[180:183], v[222:223], off offset:1056
	global_load_dwordx4 v[184:187], v[222:223], off offset:1072
	global_load_dwordx4 v[188:191], v[222:223], off offset:2048
	global_load_dwordx4 v[192:195], v[222:223], off offset:2064
	global_load_dwordx4 v[196:199], v[222:223], off offset:2080
	global_load_dwordx4 v[200:203], v[222:223], off offset:2096
	global_load_dwordx4 v[204:207], v[222:223], off offset:3072
	global_load_dwordx4 v[208:211], v[222:223], off offset:3088
	global_load_dwordx4 v[212:215], v[222:223], off offset:3104
	global_load_dwordx4 v[216:219], v[222:223], off offset:3120
	v_mul_f32_e32 v112, v144, v112
	v_mul_f32_e32 v113, v144, v113
	v_mul_f32_e32 v114, v144, v114
	v_mul_f32_e32 v115, v144, v115
	v_mul_f32_e32 v116, v144, v116
	v_mul_f32_e32 v117, v144, v117
	v_mul_f32_e32 v118, v144, v118
	v_mul_f32_e32 v119, v144, v119
	v_mul_f32_e32 v120, v144, v120
	v_mul_f32_e32 v121, v144, v121
	v_mul_f32_e32 v122, v144, v122
	v_mul_f32_e32 v123, v144, v123
	v_mul_f32_e32 v124, v144, v124
	v_mul_f32_e32 v125, v144, v125
	v_mul_f32_e32 v126, v144, v126
	v_mul_f32_e32 v127, v144, v127
	v_max_f32_e32 v112, 0, v112
	v_max_f32_e32 v113, 0, v113
	v_max_f32_e32 v114, 0, v114
	v_max_f32_e32 v115, 0, v115
	v_max_f32_e32 v116, 0, v116
	v_max_f32_e32 v117, 0, v117
	v_max_f32_e32 v118, 0, v118
	v_max_f32_e32 v119, 0, v119
	v_max_f32_e32 v120, 0, v120
	v_max_f32_e32 v121, 0, v121
	v_max_f32_e32 v122, 0, v122
	v_max_f32_e32 v123, 0, v123
	v_max_f32_e32 v124, 0, v124
	v_max_f32_e32 v125, 0, v125
	v_max_f32_e32 v126, 0, v126
	v_max_f32_e32 v127, 0, v127
	v_mul_f32_e32 v112, v112, v112
	v_mul_f32_e32 v113, v113, v113
	v_mul_f32_e32 v114, v114, v114
	v_mul_f32_e32 v115, v115, v115
	v_mul_f32_e32 v116, v116, v116
	v_mul_f32_e32 v117, v117, v117
	v_mul_f32_e32 v118, v118, v118
	v_mul_f32_e32 v119, v119, v119
	v_mul_f32_e32 v120, v120, v120
	v_mul_f32_e32 v121, v121, v121
	v_mul_f32_e32 v122, v122, v122
	v_mul_f32_e32 v123, v123, v123
	v_mul_f32_e32 v124, v124, v124
	v_mul_f32_e32 v125, v125, v125
	v_mul_f32_e32 v126, v126, v126
	v_mul_f32_e32 v127, v127, v127
	v_cvt_pk_bf16_f32 v124, v124, v125
	v_cvt_pk_bf16_f32 v125, v126, v127
	v_cvt_pk_bf16_f32 v126, v120, v121
	v_cvt_pk_bf16_f32 v127, v122, v123
	v_cvt_pk_bf16_f32 v116, v116, v117
	v_cvt_pk_bf16_f32 v117, v118, v119
	v_cvt_pk_bf16_f32 v118, v112, v113
	v_cvt_pk_bf16_f32 v119, v114, v115
	global_store_dwordx4 v[220:221], v[124:127], off
	global_store_dwordx4 v[220:221], v[116:119], off offset:256
	v_lshl_add_u64 v[220:221], v[220:221], 0, s[98:99]
	v_mul_f32_e32 v96, v145, v96
	v_mul_f32_e32 v97, v145, v97
	v_mul_f32_e32 v98, v145, v98
	v_mul_f32_e32 v99, v145, v99
	v_mul_f32_e32 v100, v145, v100
	v_mul_f32_e32 v101, v145, v101
	v_mul_f32_e32 v102, v145, v102
	v_mul_f32_e32 v103, v145, v103
	v_mul_f32_e32 v104, v145, v104
	v_mul_f32_e32 v105, v145, v105
	v_mul_f32_e32 v106, v145, v106
; __device__ __forceinline__ u32x4 pack8(const f32x4 a, const f32x4 b) { u32x4 w; w.x = cvt_pk_bf16(a[0], a[1]); w.y = cvt_pk_bf16(a[2], a[3]); w.z = cvt_pk_bf16(b[0], b[1]); w.w = cvt_pk_bf16(b[2], b[3]); return w; }
;     __device__ __forceinline__ void operator()(const f32x4 (&acc)[2][2][4][2], const Unit& u, int wr, int wc, int fr, int fq) const {
;     ...
;             for (int m = 0; m < 4; ++m) { const int row = rbase + ai * 128 + m * 16; const f32x4* sp = (const f32x4*)(SSP + (size_t)row * 16);
;                 const f32x4 s4 = (sp[0] + sp[1]) + (sp[2] + sp[3]); const float rstd = __builtin_amdgcn_rsqf(((s4[0] + s4[1]) + (s4[2] + s4[3])) * (1.0f / 1024.0f) + EPS);
; #pragma unroll
;                 for (int bj = 0; bj < 2; ++bj) { f32x4 v0 = acc[ai][bj][m][0] * rstd, v1 = acc[ai][bj][m][1] * rstd;
; #pragma unroll
;                     for (int i = 0; i < 4; ++i) { const float a = fmaxf(v0[i], 0.f), b = fmaxf(v1[i], 0.f); v0[i] = a * a; v1[i] = b * b; }
;                     *(u32x4*)(Z + (size_t)row * FF + cb + bj * 128) = pack8(v0, v1); }
	v_mul_f32_e32 v107, v145, v107
	v_mul_f32_e32 v108, v145, v108
	v_mul_f32_e32 v109, v145, v109
	v_mul_f32_e32 v110, v145, v110
	v_mul_f32_e32 v111, v145, v111
	v_max_f32_e32 v96, 0, v96
	v_max_f32_e32 v97, 0, v97
	v_max_f32_e32 v98, 0, v98
	v_max_f32_e32 v99, 0, v99
	v_max_f32_e32 v100, 0, v100
	v_max_f32_e32 v101, 0, v101
	v_max_f32_e32 v102, 0, v102
	v_max_f32_e32 v103, 0, v103
	v_max_f32_e32 v104, 0, v104
	v_max_f32_e32 v105, 0, v105
	v_max_f32_e32 v106, 0, v106
	v_max_f32_e32 v107, 0, v107
	v_max_f32_e32 v108, 0, v108
	v_max_f32_e32 v109, 0, v109
	v_max_f32_e32 v110, 0, v110
	v_max_f32_e32 v111, 0, v111
	v_mul_f32_e32 v96, v96, v96
	v_mul_f32_e32 v97, v97, v97
	v_mul_f32_e32 v98, v98, v98
	v_mul_f32_e32 v99, v99, v99
	v_mul_f32_e32 v100, v100, v100
	v_mul_f32_e32 v101, v101, v101
	v_mul_f32_e32 v102, v102, v102
	v_mul_f32_e32 v103, v103, v103
	v_mul_f32_e32 v104, v104, v104
	v_mul_f32_e32 v105, v105, v105
	v_mul_f32_e32 v106, v106, v106
	v_mul_f32_e32 v107, v107, v107
	v_mul_f32_e32 v108, v108, v108
	v_mul_f32_e32 v109, v109, v109
	v_mul_f32_e32 v110, v110, v110
	v_mul_f32_e32 v111, v111, v111
	v_cvt_pk_bf16_f32 v108, v108, v109
	v_cvt_pk_bf16_f32 v109, v110, v111
	v_cvt_pk_bf16_f32 v110, v104, v105
	v_cvt_pk_bf16_f32 v111, v106, v107
	v_cvt_pk_bf16_f32 v100, v100, v101
	v_cvt_pk_bf16_f32 v101, v102, v103
	v_cvt_pk_bf16_f32 v102, v96, v97
	v_cvt_pk_bf16_f32 v103, v98, v99
	global_store_dwordx4 v[220:221], v[108:111], off
	global_store_dwordx4 v[220:221], v[100:103], off offset:256
	v_lshl_add_u64 v[220:221], v[220:221], 0, s[98:99]
	v_mul_f32_e32 v80, v146, v80
	v_mul_f32_e32 v81, v146, v81
	v_mul_f32_e32 v82, v146, v82
	v_mul_f32_e32 v83, v146, v83
	v_mul_f32_e32 v84, v146, v84
	v_mul_f32_e32 v85, v146, v85
	v_mul_f32_e32 v86, v146, v86
	v_mul_f32_e32 v87, v146, v87
	v_mul_f32_e32 v88, v146, v88
	v_mul_f32_e32 v89, v146, v89
	v_mul_f32_e32 v90, v146, v90
	v_mul_f32_e32 v91, v146, v91
	v_mul_f32_e32 v92, v146, v92
	v_mul_f32_e32 v93, v146, v93
	v_mul_f32_e32 v94, v146, v94
	v_mul_f32_e32 v95, v146, v95
	v_max_f32_e32 v80, 0, v80
	v_max_f32_e32 v81, 0, v81
	v_max_f32_e32 v82, 0, v82
	v_max_f32_e32 v83, 0, v83
	v_max_f32_e32 v84, 0, v84
	v_max_f32_e32 v85, 0, v85
	v_max_f32_e32 v86, 0, v86
	v_max_f32_e32 v87, 0, v87
	v_max_f32_e32 v88, 0, v88
	v_max_f32_e32 v89, 0, v89
	v_max_f32_e32 v90, 0, v90
	v_max_f32_e32 v91, 0, v91
	v_max_f32_e32 v92, 0, v92
	v_max_f32_e32 v93, 0, v93
	v_max_f32_e32 v94, 0, v94
	v_max_f32_e32 v95, 0, v95
	v_mul_f32_e32 v80, v80, v80
	v_mul_f32_e32 v81, v81, v81
	v_mul_f32_e32 v82, v82, v82
	v_mul_f32_e32 v83, v83, v83
	v_mul_f32_e32 v84, v84, v84
	v_mul_f32_e32 v85, v85, v85
	v_mul_f32_e32 v86, v86, v86
	v_mul_f32_e32 v87, v87, v87
	v_mul_f32_e32 v88, v88, v88
	v_mul_f32_e32 v89, v89, v89
	v_mul_f32_e32 v90, v90, v90
	v_mul_f32_e32 v91, v91, v91
	v_mul_f32_e32 v92, v92, v92
	v_mul_f32_e32 v93, v93, v93
	v_mul_f32_e32 v94, v94, v94
	v_mul_f32_e32 v95, v95, v95
	v_cvt_pk_bf16_f32 v92, v92, v93
	v_cvt_pk_bf16_f32 v93, v94, v95
	v_cvt_pk_bf16_f32 v94, v88, v89
	v_cvt_pk_bf16_f32 v95, v90, v91
	v_cvt_pk_bf16_f32 v84, v84, v85
	v_cvt_pk_bf16_f32 v85, v86, v87
	v_cvt_pk_bf16_f32 v86, v80, v81
	v_cvt_pk_bf16_f32 v87, v82, v83
	global_store_dwordx4 v[220:221], v[92:95], off
	global_store_dwordx4 v[220:221], v[84:87], off offset:256
	v_lshl_add_u64 v[220:221], v[220:221], 0, s[98:99]
	v_mul_f32_e32 v64, v147, v64
	v_mul_f32_e32 v65, v147, v65
	v_mul_f32_e32 v66, v147, v66
	v_mul_f32_e32 v67, v147, v67
	v_mul_f32_e32 v68, v147, v68
	v_mul_f32_e32 v69, v147, v69
	v_mul_f32_e32 v70, v147, v70
	v_mul_f32_e32 v71, v147, v71
	v_mul_f32_e32 v72, v147, v72
	v_mul_f32_e32 v73, v147, v73
	v_mul_f32_e32 v74, v147, v74
	v_mul_f32_e32 v75, v147, v75
	v_mul_f32_e32 v76, v147, v76
	v_mul_f32_e32 v77, v147, v77
	v_mul_f32_e32 v78, v147, v78
	v_mul_f32_e32 v79, v147, v79
	v_max_f32_e32 v64, 0, v64
	v_max_f32_e32 v65, 0, v65
	v_max_f32_e32 v66, 0, v66
	v_max_f32_e32 v67, 0, v67
	v_max_f32_e32 v68, 0, v68
	v_max_f32_e32 v69, 0, v69
	v_max_f32_e32 v70, 0, v70
	v_max_f32_e32 v71, 0, v71
	v_max_f32_e32 v72, 0, v72
	v_max_f32_e32 v73, 0, v73
	v_max_f32_e32 v74, 0, v74
	v_max_f32_e32 v75, 0, v75
	v_max_f32_e32 v76, 0, v76
	v_max_f32_e32 v77, 0, v77
	v_max_f32_e32 v78, 0, v78
	v_max_f32_e32 v79, 0, v79
	v_mul_f32_e32 v64, v64, v64
	v_mul_f32_e32 v65, v65, v65
	v_mul_f32_e32 v66, v66, v66
	v_mul_f32_e32 v67, v67, v67
	v_mul_f32_e32 v68, v68, v68
	v_mul_f32_e32 v69, v69, v69
	v_mul_f32_e32 v70, v70, v70
	v_mul_f32_e32 v71, v71, v71
	v_mul_f32_e32 v72, v72, v72
	v_mul_f32_e32 v73, v73, v73
	v_mul_f32_e32 v74, v74, v74
	v_mul_f32_e32 v75, v75, v75
	v_mul_f32_e32 v76, v76, v76
	v_mul_f32_e32 v77, v77, v77
	v_mul_f32_e32 v78, v78, v78
	v_mul_f32_e32 v79, v79, v79
	v_cvt_pk_bf16_f32 v76, v76, v77
	v_cvt_pk_bf16_f32 v77, v78, v79
	v_cvt_pk_bf16_f32 v78, v72, v73
	v_cvt_pk_bf16_f32 v79, v74, v75
	v_cvt_pk_bf16_f32 v68, v68, v69
	v_cvt_pk_bf16_f32 v69, v70, v71
	v_cvt_pk_bf16_f32 v70, v64, v65
	v_cvt_pk_bf16_f32 v71, v66, v67
	global_store_dwordx4 v[220:221], v[76:79], off
	global_store_dwordx4 v[220:221], v[68:71], off offset:256
	v_lshl_add_u64 v[220:221], v[220:221], 0, s[100:101]
	s_waitcnt vmcnt(20)
	v_pk_add_f32 v[156:157], v[156:157], v[160:161]
	v_pk_add_f32 v[158:159], v[158:159], v[162:163]
	v_pk_add_f32 v[164:165], v[164:165], v[168:169]
	v_pk_add_f32 v[166:167], v[166:167], v[170:171]
	v_pk_add_f32 v[156:157], v[156:157], v[164:165]
	v_pk_add_f32 v[158:159], v[158:159], v[166:167]
	v_add_f32_e32 v156, v156, v157
	v_add_f32_e32 v158, v158, v159
	v_add_f32_e32 v156, v156, v158
	v_fmamk_f32 v156, v156, 0x3a800000, v154
	v_rsq_f32_e32 v144, v156
	s_waitcnt vmcnt(16)
; __device__ __forceinline__ u32x4 pack8(const f32x4 a, const f32x4 b) { u32x4 w; w.x = cvt_pk_bf16(a[0], a[1]); w.y = cvt_pk_bf16(a[2], a[3]); w.z = cvt_pk_bf16(b[0], b[1]); w.w = cvt_pk_bf16(b[2], b[3]); return w; }
;     __device__ __forceinline__ void operator()(const f32x4 (&acc)[2][2][4][2], const Unit& u, int wr, int wc, int fr, int fq) const {
;     ...
;             for (int m = 0; m < 4; ++m) { const int row = rbase + ai * 128 + m * 16; const f32x4* sp = (const f32x4*)(SSP + (size_t)row * 16);
;                 const f32x4 s4 = (sp[0] + sp[1]) + (sp[2] + sp[3]); const float rstd = __builtin_amdgcn_rsqf(((s4[0] + s4[1]) + (s4[2] + s4[3])) * (1.0f / 1024.0f) + EPS);
; #pragma unroll
;                 for (int bj = 0; bj < 2; ++bj) { f32x4 v0 = acc[ai][bj][m][0] * rstd, v1 = acc[ai][bj][m][1] * rstd;
; #pragma unroll
;                     for (int i = 0; i < 4; ++i) { const float a = fmaxf(v0[i], 0.f), b = fmaxf(v1[i], 0.f); v0[i] = a * a; v1[i] = b * b; }
;                     *(u32x4*)(Z + (size_t)row * FF + cb + bj * 128) = pack8(v0, v1); }
	v_pk_add_f32 v[172:173], v[172:173], v[176:177]
	v_pk_add_f32 v[174:175], v[174:175], v[178:179]
	v_pk_add_f32 v[180:181], v[180:181], v[184:185]
	v_pk_add_f32 v[182:183], v[182:183], v[186:187]
	v_pk_add_f32 v[172:173], v[172:173], v[180:181]
	v_pk_add_f32 v[174:175], v[174:175], v[182:183]
	v_add_f32_e32 v172, v172, v173
	v_add_f32_e32 v174, v174, v175
	v_add_f32_e32 v172, v172, v174
	v_fmamk_f32 v172, v172, 0x3a800000, v154
	v_rsq_f32_e32 v145, v172
	s_waitcnt vmcnt(12)
	v_pk_add_f32 v[188:189], v[188:189], v[192:193]
	v_pk_add_f32 v[190:191], v[190:191], v[194:195]
	v_pk_add_f32 v[196:197], v[196:197], v[200:201]
	v_pk_add_f32 v[198:199], v[198:199], v[202:203]
	v_pk_add_f32 v[188:189], v[188:189], v[196:197]
	v_pk_add_f32 v[190:191], v[190:191], v[198:199]
	v_add_f32_e32 v188, v188, v189
	v_add_f32_e32 v190, v190, v191
	v_add_f32_e32 v188, v188, v190
	v_fmamk_f32 v188, v188, 0x3a800000, v154
	v_rsq_f32_e32 v146, v188
	s_waitcnt vmcnt(8)
	v_pk_add_f32 v[204:205], v[204:205], v[208:209]
	v_pk_add_f32 v[206:207], v[206:207], v[210:211]
	v_pk_add_f32 v[212:213], v[212:213], v[216:217]
	v_pk_add_f32 v[214:215], v[214:215], v[218:219]
	v_pk_add_f32 v[204:205], v[204:205], v[212:213]
	v_pk_add_f32 v[206:207], v[206:207], v[214:215]
	v_add_f32_e32 v204, v204, v205
	v_add_f32_e32 v206, v206, v207
	v_add_f32_e32 v204, v204, v206
	v_fmamk_f32 v204, v204, 0x3a800000, v154
	v_rsq_f32_e32 v147, v204
	v_mul_f32_e32 v48, v144, v48
	v_mul_f32_e32 v49, v144, v49
	v_mul_f32_e32 v50, v144, v50
	v_mul_f32_e32 v51, v144, v51
	v_mul_f32_e32 v52, v144, v52
	v_mul_f32_e32 v53, v144, v53
	v_mul_f32_e32 v54, v144, v54
	v_mul_f32_e32 v55, v144, v55
	v_mul_f32_e32 v56, v144, v56
	v_mul_f32_e32 v57, v144, v57
	v_mul_f32_e32 v58, v144, v58
	v_mul_f32_e32 v59, v144, v59
	v_mul_f32_e32 v60, v144, v60
	v_mul_f32_e32 v61, v144, v61
	v_mul_f32_e32 v62, v144, v62
	v_mul_f32_e32 v63, v144, v63
	v_max_f32_e32 v48, 0, v48
	v_max_f32_e32 v49, 0, v49
	v_max_f32_e32 v50, 0, v50
	v_max_f32_e32 v51, 0, v51
	v_max_f32_e32 v52, 0, v52
	v_max_f32_e32 v53, 0, v53
	v_max_f32_e32 v54, 0, v54
	v_max_f32_e32 v55, 0, v55
	v_max_f32_e32 v56, 0, v56
	v_max_f32_e32 v57, 0, v57
	v_max_f32_e32 v58, 0, v58
	v_max_f32_e32 v59, 0, v59
	v_max_f32_e32 v60, 0, v60
	v_max_f32_e32 v61, 0, v61
	v_max_f32_e32 v62, 0, v62
	v_max_f32_e32 v63, 0, v63
	v_mul_f32_e32 v48, v48, v48
	v_mul_f32_e32 v49, v49, v49
	v_mul_f32_e32 v50, v50, v50
	v_mul_f32_e32 v51, v51, v51
	v_mul_f32_e32 v52, v52, v52
	v_mul_f32_e32 v53, v53, v53
	v_mul_f32_e32 v54, v54, v54
	v_mul_f32_e32 v55, v55, v55
	v_mul_f32_e32 v56, v56, v56
	v_mul_f32_e32 v57, v57, v57
	v_mul_f32_e32 v58, v58, v58
	v_mul_f32_e32 v59, v59, v59
	v_mul_f32_e32 v60, v60, v60
	v_mul_f32_e32 v61, v61, v61
	v_mul_f32_e32 v62, v62, v62
	v_mul_f32_e32 v63, v63, v63
	v_cvt_pk_bf16_f32 v60, v60, v61
	v_cvt_pk_bf16_f32 v61, v62, v63
	v_cvt_pk_bf16_f32 v62, v56, v57
	v_cvt_pk_bf16_f32 v63, v58, v59
	v_cvt_pk_bf16_f32 v52, v52, v53
	v_cvt_pk_bf16_f32 v53, v54, v55
	v_cvt_pk_bf16_f32 v54, v48, v49
	v_cvt_pk_bf16_f32 v55, v50, v51
	global_store_dwordx4 v[220:221], v[60:63], off
	global_store_dwordx4 v[220:221], v[52:55], off offset:256
	v_lshl_add_u64 v[220:221], v[220:221], 0, s[98:99]
	v_mul_f32_e32 v32, v145, v32
	v_mul_f32_e32 v33, v145, v33
	v_mul_f32_e32 v34, v145, v34
	v_mul_f32_e32 v35, v145, v35
	v_mul_f32_e32 v36, v145, v36
	v_mul_f32_e32 v37, v145, v37
	v_mul_f32_e32 v38, v145, v38
	v_mul_f32_e32 v39, v145, v39
	v_mul_f32_e32 v40, v145, v40
	v_mul_f32_e32 v41, v145, v41
	v_mul_f32_e32 v42, v145, v42
	v_mul_f32_e32 v43, v145, v43
	v_mul_f32_e32 v44, v145, v44
	v_mul_f32_e32 v45, v145, v45
	v_mul_f32_e32 v46, v145, v46
	v_mul_f32_e32 v47, v145, v47
	v_max_f32_e32 v32, 0, v32
	v_max_f32_e32 v33, 0, v33
	v_max_f32_e32 v34, 0, v34
	v_max_f32_e32 v35, 0, v35
	v_max_f32_e32 v36, 0, v36
	v_max_f32_e32 v37, 0, v37
	v_max_f32_e32 v38, 0, v38
	v_max_f32_e32 v39, 0, v39
	v_max_f32_e32 v40, 0, v40
	v_max_f32_e32 v41, 0, v41
	v_max_f32_e32 v42, 0, v42
	v_max_f32_e32 v43, 0, v43
	v_max_f32_e32 v44, 0, v44
	v_max_f32_e32 v45, 0, v45
	v_max_f32_e32 v46, 0, v46
	v_max_f32_e32 v47, 0, v47
	v_mul_f32_e32 v32, v32, v32
	v_mul_f32_e32 v33, v33, v33
	v_mul_f32_e32 v34, v34, v34
	v_mul_f32_e32 v35, v35, v35
	v_mul_f32_e32 v36, v36, v36
	v_mul_f32_e32 v37, v37, v37
; #define PG8_WAIT_V(n) asm volatile("s_waitcnt vmcnt(" #n ")" ::: "memory")
; #define PG8_BAR __builtin_amdgcn_s_barrier()
; __device__ __forceinline__ u32x4 pack8(const f32x4 a, const f32x4 b) { u32x4 w; w.x = cvt_pk_bf16(a[0], a[1]); w.y = cvt_pk_bf16(a[2], a[3]); w.z = cvt_pk_bf16(b[0], b[1]); w.w = cvt_pk_bf16(b[2], b[3]); return w; }
; template <class Epi, class Sched, bool ALIGN_EPI = false, bool SP2 = false>
; __device__ __forceinline__ void gemm_phase(PG8_LAS unsigned char* lds, const Gemm g, const Sched& S, const Epi& E) {
;     ...
;     PG8_WAIT_V(0);
;     if constexpr (!ALIGN_EPI) { if (wr == 0) PG8_BAR; }
;     PG8_BAR;
;     __device__ __forceinline__ void operator()(const f32x4 (&acc)[2][2][4][2], const Unit& u, int wr, int wc, int fr, int fq) const {
;     ...
;                 for (int bj = 0; bj < 2; ++bj) { f32x4 v0 = acc[ai][bj][m][0] * rstd, v1 = acc[ai][bj][m][1] * rstd;
; #pragma unroll
;                     for (int i = 0; i < 4; ++i) { const float a = fmaxf(v0[i], 0.f), b = fmaxf(v1[i], 0.f); v0[i] = a * a; v1[i] = b * b; }
;                     *(u32x4*)(Z + (size_t)row * FF + cb + bj * 128) = pack8(v0, v1); }
	v_mul_f32_e32 v38, v38, v38
	v_mul_f32_e32 v39, v39, v39
	v_mul_f32_e32 v40, v40, v40
	v_mul_f32_e32 v41, v41, v41
	v_mul_f32_e32 v42, v42, v42
	v_mul_f32_e32 v43, v43, v43
	v_mul_f32_e32 v44, v44, v44
	v_mul_f32_e32 v45, v45, v45
	v_mul_f32_e32 v46, v46, v46
	v_mul_f32_e32 v47, v47, v47
	v_cvt_pk_bf16_f32 v228, v44, v45
	v_cvt_pk_bf16_f32 v229, v46, v47
	v_cvt_pk_bf16_f32 v230, v40, v41
	v_cvt_pk_bf16_f32 v231, v42, v43
	v_cvt_pk_bf16_f32 v232, v36, v37
	v_cvt_pk_bf16_f32 v233, v38, v39
	v_cvt_pk_bf16_f32 v234, v32, v33
	v_cvt_pk_bf16_f32 v235, v34, v35
	v_mul_f32_e32 v16, v146, v16
	v_mul_f32_e32 v17, v146, v17
	v_mul_f32_e32 v18, v146, v18
	v_mul_f32_e32 v19, v146, v19
	v_mul_f32_e32 v20, v146, v20
	v_mul_f32_e32 v21, v146, v21
	v_mul_f32_e32 v22, v146, v22
	v_mul_f32_e32 v23, v146, v23
	v_mul_f32_e32 v24, v146, v24
	v_mul_f32_e32 v25, v146, v25
	v_mul_f32_e32 v26, v146, v26
	v_mul_f32_e32 v27, v146, v27
	v_mul_f32_e32 v28, v146, v28
	v_mul_f32_e32 v29, v146, v29
	v_mul_f32_e32 v30, v146, v30
	v_mul_f32_e32 v31, v146, v31
	v_max_f32_e32 v16, 0, v16
	v_max_f32_e32 v17, 0, v17
	v_max_f32_e32 v18, 0, v18
	v_max_f32_e32 v19, 0, v19
	v_max_f32_e32 v20, 0, v20
	v_max_f32_e32 v21, 0, v21
	v_max_f32_e32 v22, 0, v22
	v_max_f32_e32 v23, 0, v23
	v_max_f32_e32 v24, 0, v24
	v_max_f32_e32 v25, 0, v25
	v_max_f32_e32 v26, 0, v26
	v_max_f32_e32 v27, 0, v27
	v_max_f32_e32 v28, 0, v28
	v_max_f32_e32 v29, 0, v29
	v_max_f32_e32 v30, 0, v30
	v_max_f32_e32 v31, 0, v31
	v_mul_f32_e32 v16, v16, v16
	v_mul_f32_e32 v17, v17, v17
	v_mul_f32_e32 v18, v18, v18
	v_mul_f32_e32 v19, v19, v19
	v_mul_f32_e32 v20, v20, v20
	v_mul_f32_e32 v21, v21, v21
	v_mul_f32_e32 v22, v22, v22
	v_mul_f32_e32 v23, v23, v23
	v_mul_f32_e32 v24, v24, v24
	v_mul_f32_e32 v25, v25, v25
	v_mul_f32_e32 v26, v26, v26
	v_mul_f32_e32 v27, v27, v27
	v_mul_f32_e32 v28, v28, v28
	v_mul_f32_e32 v29, v29, v29
	v_mul_f32_e32 v30, v30, v30
	v_mul_f32_e32 v31, v31, v31
	v_cvt_pk_bf16_f32 v236, v28, v29
	v_cvt_pk_bf16_f32 v237, v30, v31
	v_cvt_pk_bf16_f32 v238, v24, v25
	v_cvt_pk_bf16_f32 v239, v26, v27
	v_cvt_pk_bf16_f32 v240, v20, v21
	v_cvt_pk_bf16_f32 v241, v22, v23
	v_cvt_pk_bf16_f32 v242, v16, v17
	v_cvt_pk_bf16_f32 v243, v18, v19
	v_mul_f32_e32 v0, v147, v0
	v_mul_f32_e32 v1, v147, v1
	v_mul_f32_e32 v2, v147, v2
	v_mul_f32_e32 v3, v147, v3
	v_mul_f32_e32 v4, v147, v4
	v_mul_f32_e32 v5, v147, v5
	v_mul_f32_e32 v6, v147, v6
	v_mul_f32_e32 v7, v147, v7
	v_mul_f32_e32 v8, v147, v8
	v_mul_f32_e32 v9, v147, v9
	v_mul_f32_e32 v10, v147, v10
	v_mul_f32_e32 v11, v147, v11
	v_mul_f32_e32 v12, v147, v12
	v_mul_f32_e32 v13, v147, v13
	v_mul_f32_e32 v14, v147, v14
	v_mul_f32_e32 v15, v147, v15
	v_max_f32_e32 v0, 0, v0
	v_max_f32_e32 v1, 0, v1
	v_max_f32_e32 v2, 0, v2
	v_max_f32_e32 v3, 0, v3
	v_max_f32_e32 v4, 0, v4
	v_max_f32_e32 v5, 0, v5
	v_max_f32_e32 v6, 0, v6
	v_max_f32_e32 v7, 0, v7
	v_max_f32_e32 v8, 0, v8
	v_max_f32_e32 v9, 0, v9
	v_max_f32_e32 v10, 0, v10
	v_max_f32_e32 v11, 0, v11
	v_max_f32_e32 v12, 0, v12
	v_max_f32_e32 v13, 0, v13
	v_max_f32_e32 v14, 0, v14
	v_max_f32_e32 v15, 0, v15
	v_mul_f32_e32 v0, v0, v0
	v_mul_f32_e32 v1, v1, v1
	v_mul_f32_e32 v2, v2, v2
	v_mul_f32_e32 v3, v3, v3
	v_mul_f32_e32 v4, v4, v4
	v_mul_f32_e32 v5, v5, v5
	v_mul_f32_e32 v6, v6, v6
	v_mul_f32_e32 v7, v7, v7
	v_mul_f32_e32 v8, v8, v8
	v_mul_f32_e32 v9, v9, v9
	v_mul_f32_e32 v10, v10, v10
	v_mul_f32_e32 v11, v11, v11
	v_mul_f32_e32 v12, v12, v12
	v_mul_f32_e32 v13, v13, v13
	v_mul_f32_e32 v14, v14, v14
	v_mul_f32_e32 v15, v15, v15
	v_cvt_pk_bf16_f32 v244, v12, v13
	v_cvt_pk_bf16_f32 v245, v14, v15
	v_cvt_pk_bf16_f32 v246, v8, v9
	v_cvt_pk_bf16_f32 v247, v10, v11
	v_cvt_pk_bf16_f32 v248, v4, v5
	v_cvt_pk_bf16_f32 v249, v6, v7
	v_cvt_pk_bf16_f32 v250, v0, v1
	v_cvt_pk_bf16_f32 v251, v2, v3
	s_andn2_b64 vcc, exec, s[4:5]
	s_mov_b64 s[4:5], -1
	s_cbranch_vccnz .LBB0_1536
	s_andn2_b64 vcc, exec, s[6:7]
	s_cbranch_vccnz .LBB0_1535
	s_barrier
	s_branch .LBB0_1535
.LBB0_1546:
	global_store_dwordx4 v227, v[228:231], s[72:73]
	global_store_dwordx4 v227, v[232:235], s[72:73] offset:256
	global_store_dwordx4 v227, v[236:239], s[74:75]
	global_store_dwordx4 v227, v[240:243], s[74:75] offset:256
	global_store_dwordx4 v227, v[244:247], s[76:77]
	global_store_dwordx4 v227, v[248:251], s[76:77] offset:256
	s_waitcnt vmcnt(0)
	s_barrier
